# v13 + first-half PV transpose-read burst issued before the LDS write block
# baseline (speedup 1.0000x reference)
; #define SBAR() __builtin_amdgcn_sched_barrier(0)
; __device__ __forceinline__ void finishSM(f32x16& p0, f32x16& p1, float alpha, float& l_reg, bf16x8& pa0, bf16x8& pa1, bf16x8& pa2, bf16x8& pa3) {
; #pragma unroll
;   for (int r = 0; r < 16; ++r) p1[r] = __builtin_amdgcn_exp2f(p1[r]);
;   float ps = 0;
; #pragma unroll
;   for (int r = 0; r < 16; ++r) ps += p0[r];
; #pragma unroll
;   for (int r = 0; r < 16; ++r) ps += p1[r];
;   { auto rr = __builtin_amdgcn_permlane32_swap(__float_as_uint(ps), __float_as_uint(ps), false, false);
;     ps = __uint_as_float(rr[0]) + __uint_as_float(rr[1]); }
;   l_reg = l_reg * alpha + ps;
;   PK4(p0, 0, pa0); PK4(p0, 8, pa1); PK4(p1, 0, pa2); PK4(p1, 8, pa3);
; }
;   p0 = f32x16{}; p1 = f32x16{};
; #pragma unroll
;   for (int d0 = DLO; d0 < DHI; ++d0) { int cb = (d0 * 16 + hi * 8) * 2;
;     bf16x8 b0 = *reinterpret_cast<const bf16x8*>((const char*)Ks + KSWZ(r32, cb));
;     bf16x8 b1 = *reinterpret_cast<const bf16x8*>((const char*)Ks + KSWZ(32 + r32, cb));
;     p0 = __builtin_amdgcn_mfma_f32_32x32x16_bf16(b0, qr[d0], p0, 0, 0, 0);
;     p1 = __builtin_amdgcn_mfma_f32_32x32x16_bf16(b1, qr[d0], p1, 0, 0, 0); }
; }
; template <int D0> __device__ __forceinline__ void pv_one(f32x16& od, int vb, bf16x8 pa0, bf16x8 pa1, bf16x8 pa2, bf16x8 pa3) {
;   const s16x4 l0 = tr_read<v_rd_off(D0, 0, 0)>(vb), h0 = tr_read<v_rd_off(D0, 0, 1)>(vb), l1 = tr_read<v_rd_off(D0, 1, 0)>(vb), h1 = tr_read<v_rd_off(D0, 1, 1)>(vb);
;   const s16x4 l2 = tr_read<v_rd_off(D0, 2, 0)>(vb), h2 = tr_read<v_rd_off(D0, 2, 1)>(vb), l3 = tr_read<v_rd_off(D0, 3, 0)>(vb), h3 = tr_read<v_rd_off(D0, 3, 1)>(vb);
;   asm volatile("s_waitcnt lgkmcnt(0)" ::: "memory"); SBAR();
;     ...
;   od = __builtin_amdgcn_mfma_f32_32x32x16_bf16(pa0, PK(l0, h0), od, 0, 0, 0);
;   od = __builtin_amdgcn_mfma_f32_32x32x16_bf16(pa1, PK(l1, h1), od, 0, 0, 0);
;   od = __builtin_amdgcn_mfma_f32_32x32x16_bf16(pa2, PK(l2, h2), od, 0, 0, 0);
;   od = __builtin_amdgcn_mfma_f32_32x32x16_bf16(pa3, PK(l3, h3), od, 0, 0, 0);
.LBB0_1002:
	ds_read_b128 v[66:69], v190 offset:49152
	ds_read_b128 v[70:73], v190 offset:57344
	ds_read_b128 v[186:189], v194 offset:49152
	ds_read_b128 v[208:211], v194 offset:57344
	ds_read_b128 v[232:235], v195 offset:49152
	ds_read_b128 v[236:239], v195 offset:57344
	ds_read_b128 v[240:243], v196 offset:49152
	ds_read_b128 v[244:247], v196 offset:57344
	v_add_f32_e32 v146, 0, v161
	v_add_f32_e32 v146, v167, v146
	v_add_f32_e32 v146, v147, v146
	s_waitcnt lgkmcnt(7)
	v_mfma_f32_32x32x16_bf16 v[82:97], v[66:69], v[102:105], 0
	v_add_f32_e32 v146, v166, v146
	v_add_f32_e32 v146, v148, v146
	v_add_f32_e32 v146, v160, v146
	v_add_f32_e32 v146, v149, v146
	v_add_f32_e32 v146, v159, v146
	v_add_f32_e32 v146, v156, v146
	s_waitcnt lgkmcnt(6)
	v_mfma_f32_32x32x16_bf16 v[66:81], v[70:73], v[102:105], 0
	v_add_f32_e32 v146, v158, v146
	v_add_f32_e32 v146, v154, v146
	v_add_f32_e32 v146, v157, v146
	v_exp_f32_e32 v142, v142
	v_add_f32_e32 v146, v152, v146
	v_exp_f32_e32 v143, v143
	v_add_f32_e32 v146, v155, v146
	s_waitcnt lgkmcnt(5)
	v_mfma_f32_32x32x16_bf16 v[82:97], v[186:189], v[98:101], v[82:97]
	v_exp_f32_e32 v140, v140
	v_add_f32_e32 v146, v151, v146
	v_exp_f32_e32 v141, v141
	v_add_f32_e32 v146, v153, v146
	v_exp_f32_e32 v134, v134
	v_add_f32_e32 v146, v142, v146
	v_exp_f32_e32 v135, v135
	s_waitcnt lgkmcnt(4)
	v_mfma_f32_32x32x16_bf16 v[66:81], v[208:211], v[98:101], v[66:81]
	v_add_f32_e32 v146, v143, v146
	v_exp_f32_e32 v132, v132
	v_add_f32_e32 v146, v140, v146
	v_exp_f32_e32 v133, v133
	v_add_f32_e32 v146, v141, v146
	v_exp_f32_e32 v130, v130
	s_waitcnt lgkmcnt(3)
	v_mfma_f32_32x32x16_bf16 v[82:97], v[232:235], v[106:109], v[82:97]
	v_add_f32_e32 v146, v134, v146
	v_exp_f32_e32 v131, v131
	v_add_f32_e32 v146, v135, v146
	v_exp_f32_e32 v144, v144
	v_add_f32_e32 v146, v132, v146
	v_exp_f32_e32 v145, v145
	v_add_f32_e32 v146, v133, v146
	s_waitcnt lgkmcnt(2)
	v_mfma_f32_32x32x16_bf16 v[66:81], v[236:239], v[106:109], v[66:81]
	v_exp_f32_e32 v138, v138
	v_add_f32_e32 v146, v130, v146
	v_exp_f32_e32 v139, v139
	v_add_f32_e32 v146, v131, v146
	v_exp_f32_e32 v136, v136
	v_add_f32_e32 v146, v144, v146
	s_waitcnt lgkmcnt(1)
	v_mfma_f32_32x32x16_bf16 v[82:97], v[240:243], v[110:113], v[82:97]
	v_exp_f32_e32 v137, v137
	v_add_f32_e32 v146, v145, v146
	v_add_f32_e32 v146, v138, v146
	v_add_f32_e32 v146, v139, v146
	v_add_f32_e32 v146, v136, v146
	v_add_f32_e32 v207, v137, v146
	v_cvt_pk_bf16_f32 v146, v161, v167
	s_waitcnt lgkmcnt(0)
	v_mfma_f32_32x32x16_bf16 v[66:81], v[244:247], v[110:113], v[66:81]
	v_mov_b32_e32 v208, v207
	v_cvt_pk_bf16_f32 v147, v147, v166
	v_cvt_pk_bf16_f32 v148, v148, v160
	s_nop 1
	v_permlane32_swap_b32_e32 v207, v208
	v_cvt_pk_bf16_f32 v149, v149, v159
	v_permlane32_swap_b32_e32 v146, v148
	v_cvt_pk_bf16_f32 v156, v156, v158
	v_cvt_pk_bf16_f32 v157, v154, v157
	v_cvt_pk_bf16_f32 v158, v152, v155
	v_cvt_pk_bf16_f32 v159, v151, v153
	v_cvt_pk_bf16_f32 v152, v142, v143
	v_cvt_pk_bf16_f32 v153, v140, v141
	v_cvt_pk_bf16_f32 v154, v134, v135
	v_cvt_pk_bf16_f32 v155, v132, v133
	v_cvt_pk_bf16_f32 v186, v130, v131
	v_cvt_pk_bf16_f32 v187, v144, v145
	v_cvt_pk_bf16_f32 v188, v138, v139
	v_cvt_pk_bf16_f32 v189, v136, v137
	v_permlane32_swap_b32_e32 v147, v149
	v_permlane32_swap_b32_e32 v156, v158
	v_permlane32_swap_b32_e32 v157, v159
	v_permlane32_swap_b32_e32 v152, v154
	v_permlane32_swap_b32_e32 v153, v155
	v_permlane32_swap_b32_e32 v186, v188
	v_permlane32_swap_b32_e32 v187, v189
	ds_read_b64_tr_b16 v[210:211], v176 offset:0
	ds_read_b64_tr_b16 v[212:213], v176 offset:0x800
	ds_read_b64_tr_b16 v[214:215], v176 offset:0x1000
	ds_read_b64_tr_b16 v[216:217], v176 offset:0x1800
	ds_read_b64_tr_b16 v[218:219], v176 offset:0x2000
	ds_read_b64_tr_b16 v[220:221], v176 offset:0x2800
	ds_read_b64_tr_b16 v[222:223], v176 offset:0x3000
	ds_read_b64_tr_b16 v[224:225], v176 offset:0x3800
	s_waitcnt vmcnt(0)
	ds_write_b128 v192, v[114:117]
	ds_write_b128 v193, v[118:121]
	ds_write_b128 v177, v[122:125] offset:32768
	ds_write_b128 v191, v[126:129] offset:32768
	v_lshl_add_u64 v[168:169], v[164:165], 0, v[0:1]
	s_mov_b32 s1, 0x18fb0000
	v_add_co_u32_e32 v130, vcc, s1, v168
	s_mov_b32 s1, 0x18ff8000
	s_nop 0
	v_addc_co_u32_e32 v131, vcc, 0, v169, vcc
	v_add_co_u32_e32 v134, vcc, s1, v168
	v_lshl_add_u64 v[166:167], v[162:163], 0, v[0:1]
	s_nop 0
	v_addc_co_u32_e32 v135, vcc, 0, v169, vcc
	s_mov_b32 s1, 0x1f648000
	v_add_co_u32_e32 v138, vcc, s1, v166
	s_mov_b32 s1, 0x1f654000
	s_nop 0
	v_addc_co_u32_e32 v139, vcc, 0, v167, vcc
	v_add_co_u32_e32 v142, vcc, s1, v166
	global_load_dwordx4 v[130:133], v[130:131], off
	s_nop 0
	global_load_dwordx4 v[134:137], v[134:135], off
	v_addc_co_u32_e32 v143, vcc, 0, v167, vcc
	global_load_dwordx4 v[138:141], v[138:139], off
	s_nop 0
	global_load_dwordx4 v[142:145], v[142:143], off
	s_waitcnt lgkmcnt(8)
	s_nop 0
	v_mfma_f32_32x32x16_bf16 v[2:17], v[146:149], v[210:213], v[2:17]
	ds_read_b64_tr_b16 v[210:211], v176 offset:0x200
	ds_read_b64_tr_b16 v[212:213], v176 offset:0xa00
	v_mfma_f32_32x32x16_bf16 v[2:17], v[156:159], v[214:217], v[2:17]
	ds_read_b64_tr_b16 v[214:215], v176 offset:0x1200
	ds_read_b64_tr_b16 v[216:217], v176 offset:0x1a00
	s_waitcnt lgkmcnt(8)
; #define SBAR() __builtin_amdgcn_sched_barrier(0)
; __device__ __forceinline__ void partialSM(f32x16& p0, f32x16& p1, float& m_reg, float& mn, float& alpha) {
;   constexpr float C = SCALE * 1.4426950408889634f;
;   float pmax = p0[0];
; #pragma unroll
;   for (int r = 1; r < 16; ++r) pmax = fmaxf(pmax, p0[r]);
; #pragma unroll
;   for (int r = 0; r < 16; ++r) pmax = fmaxf(pmax, p1[r]);
;   { auto rr = __builtin_amdgcn_permlane32_swap(__float_as_uint(pmax), __float_as_uint(pmax), false, false);
;     pmax = fmaxf(__uint_as_float(rr[0]), __uint_as_float(rr[1])); }
;   if (__builtin_expect(__all(pmax - m_reg <= THR / SCALE), 1)) { mn = m_reg; alpha = 1.f; }
;   else { mn = fmaxf(m_reg, pmax); alpha = __builtin_amdgcn_exp2f((m_reg - mn) * C); m_reg = mn; }
; template <int D0> __device__ __forceinline__ void pv_one(f32x16& od, int vb, bf16x8 pa0, bf16x8 pa1, bf16x8 pa2, bf16x8 pa3) {
;   const s16x4 l0 = tr_read<v_rd_off(D0, 0, 0)>(vb), h0 = tr_read<v_rd_off(D0, 0, 1)>(vb), l1 = tr_read<v_rd_off(D0, 1, 0)>(vb), h1 = tr_read<v_rd_off(D0, 1, 1)>(vb);
;   const s16x4 l2 = tr_read<v_rd_off(D0, 2, 0)>(vb), h2 = tr_read<v_rd_off(D0, 2, 1)>(vb), l3 = tr_read<v_rd_off(D0, 3, 0)>(vb), h3 = tr_read<v_rd_off(D0, 3, 1)>(vb);
;   asm volatile("s_waitcnt lgkmcnt(0)" ::: "memory"); SBAR();
;     ...
;   od = __builtin_amdgcn_mfma_f32_32x32x16_bf16(pa0, PK(l0, h0), od, 0, 0, 0);
;   od = __builtin_amdgcn_mfma_f32_32x32x16_bf16(pa1, PK(l1, h1), od, 0, 0, 0);
;   od = __builtin_amdgcn_mfma_f32_32x32x16_bf16(pa2, PK(l2, h2), od, 0, 0, 0);
;   od = __builtin_amdgcn_mfma_f32_32x32x16_bf16(pa3, PK(l3, h3), od, 0, 0, 0);
;     ...
; }
; __device__ __forceinline__ void pv_d0(f32x16* o, int vb, bf16x8 pa0, bf16x8 pa1, bf16x8 pa2, bf16x8 pa3) {
;   pv_one<0>(o[0], vb, pa0, pa1, pa2, pa3); pv_one<1>(o[1], vb, pa0, pa1, pa2, pa3); pv_one<2>(o[2], vb, pa0, pa1, pa2, pa3); pv_one<3>(o[3], vb, pa0, pa1, pa2, pa3);
	v_mfma_f32_32x32x16_bf16 v[2:17], v[152:155], v[218:221], v[2:17]
	ds_read_b64_tr_b16 v[218:219], v176 offset:0x2200
	ds_read_b64_tr_b16 v[220:221], v176 offset:0x2a00
	v_mfma_f32_32x32x16_bf16 v[2:17], v[186:189], v[222:225], v[2:17]
	ds_read_b64_tr_b16 v[222:223], v176 offset:0x3200
	ds_read_b64_tr_b16 v[224:225], v176 offset:0x3a00
	s_waitcnt lgkmcnt(4)
	v_mfma_f32_32x32x16_bf16 v[50:65], v[146:149], v[210:213], v[50:65]
	ds_read_b64_tr_b16 v[210:211], v176 offset:0x400
	ds_read_b64_tr_b16 v[212:213], v176 offset:0xc00
	v_mfma_f32_32x32x16_bf16 v[50:65], v[156:159], v[214:217], v[50:65]
	ds_read_b64_tr_b16 v[214:215], v176 offset:0x1400
	ds_read_b64_tr_b16 v[216:217], v176 offset:0x1c00
	s_waitcnt lgkmcnt(4)
	v_mfma_f32_32x32x16_bf16 v[50:65], v[152:155], v[218:221], v[50:65]
	ds_read_b64_tr_b16 v[218:219], v176 offset:0x2400
	ds_read_b64_tr_b16 v[220:221], v176 offset:0x2c00
	v_mfma_f32_32x32x16_bf16 v[50:65], v[186:189], v[222:225], v[50:65]
	ds_read_b64_tr_b16 v[222:223], v176 offset:0x3400
	ds_read_b64_tr_b16 v[224:225], v176 offset:0x3c00
	s_waitcnt lgkmcnt(4)
	v_mfma_f32_32x32x16_bf16 v[34:49], v[146:149], v[210:213], v[34:49]
	ds_read_b64_tr_b16 v[210:211], v176 offset:0x600
	ds_read_b64_tr_b16 v[212:213], v176 offset:0xe00
	v_mfma_f32_32x32x16_bf16 v[34:49], v[156:159], v[214:217], v[34:49]
	ds_read_b64_tr_b16 v[214:215], v176 offset:0x1600
	ds_read_b64_tr_b16 v[216:217], v176 offset:0x1e00
	s_waitcnt lgkmcnt(4)
	v_mfma_f32_32x32x16_bf16 v[34:49], v[152:155], v[218:221], v[34:49]
	ds_read_b64_tr_b16 v[218:219], v176 offset:0x2600
	ds_read_b64_tr_b16 v[220:221], v176 offset:0x2e00
	v_mfma_f32_32x32x16_bf16 v[34:49], v[186:189], v[222:225], v[34:49]
	ds_read_b64_tr_b16 v[222:223], v176 offset:0x3600
	ds_read_b64_tr_b16 v[224:225], v176 offset:0x3e00
	s_waitcnt lgkmcnt(4)
	v_mfma_f32_32x32x16_bf16 v[18:33], v[146:149], v[210:213], v[18:33]
	v_max_f32_e32 v146, v83, v83
	v_max_f32_e32 v147, v82, v82
	v_max_f32_e32 v146, v147, v146
	v_max3_f32 v146, v146, v84, v85
	v_max3_f32 v146, v146, v86, v87
	v_max3_f32 v146, v146, v88, v89
	v_max3_f32 v146, v146, v90, v91
	v_max3_f32 v146, v146, v92, v93
	v_max3_f32 v146, v146, v94, v95
	v_mfma_f32_32x32x16_bf16 v[18:33], v[156:159], v[214:217], v[18:33]
	v_max3_f32 v146, v146, v96, v97
	v_max3_f32 v146, v146, v66, v67
	v_max3_f32 v146, v146, v68, v69
	v_max3_f32 v146, v146, v70, v71
	v_max3_f32 v146, v146, v72, v73
	v_max3_f32 v146, v146, v74, v75
	v_max3_f32 v146, v146, v76, v77
	v_max3_f32 v146, v146, v78, v79
	s_waitcnt lgkmcnt(0)
	v_mfma_f32_32x32x16_bf16 v[18:33], v[152:155], v[218:221], v[18:33]
	v_max3_f32 v146, v146, v80, v81
	v_mov_b32_e32 v147, v146
	s_nop 1
	v_permlane32_swap_b32_e32 v146, v147
	v_max_f32_e32 v147, v147, v147
	v_max_f32_e32 v146, v146, v146
	v_max_f32_e32 v146, v146, v147
	v_sub_f32_e32 v147, v146, v150
	v_cmp_ge_f32_e32 vcc, s63, v147
	v_max_f32_e32 v147, v150, v150
	v_max_f32_e32 v146, v147, v146
	v_mfma_f32_32x32x16_bf16 v[18:33], v[186:189], v[222:225], v[18:33]
	v_sub_f32_e32 v147, v150, v146
	v_mul_f32_e32 v147, 0x3e0293ee, v147
	v_exp_f32_e32 v147, v147
	s_cmp_eq_u64 vcc, exec
	s_cselect_b64 s[8:9], -1, 0
	s_waitcnt vmcnt(4)
	v_cndmask_b32_e64 v209, v147, 1.0, s[8:9]
	v_cmp_gt_f32_e32 vcc, 1.0, v209
	s_cbranch_vccz .LBB0_1006
	s_and_saveexec_b64 s[2:3], s[6:7]
	ds_write_b32 v173, v209 offset:128
	s_or_b64 exec, exec, s[2:3]
	s_waitcnt lgkmcnt(0)
	v_add_u32_e32 v147, s15, v172
	ds_read_b128 v[152:155], v147 offset:224
	ds_read_b128 v[156:159], v147 offset:192
	ds_read_b128 v[186:189], v147 offset:160
	ds_read_b128 v[210:213], v147 offset:128
	s_waitcnt lgkmcnt(3)
	v_pk_mul_f32 v[14:15], v[14:15], v[152:153]
	s_waitcnt lgkmcnt(2)
	v_pk_mul_f32 v[10:11], v[10:11], v[156:157]
	s_waitcnt lgkmcnt(1)
	v_pk_mul_f32 v[6:7], v[6:7], v[186:187]
	v_pk_mul_f32 v[16:17], v[16:17], v[154:155]
	v_pk_mul_f32 v[12:13], v[12:13], v[158:159]
	v_pk_mul_f32 v[8:9], v[8:9], v[188:189]
	s_waitcnt lgkmcnt(0)
	v_pk_mul_f32 v[4:5], v[4:5], v[212:213]
	v_pk_mul_f32 v[2:3], v[2:3], v[210:211]
	v_pk_mul_f32 v[62:63], v[62:63], v[152:153]
	v_pk_mul_f32 v[58:59], v[58:59], v[156:157]
	v_pk_mul_f32 v[54:55], v[54:55], v[186:187]
	v_pk_mul_f32 v[64:65], v[64:65], v[154:155]
	v_pk_mul_f32 v[60:61], v[60:61], v[158:159]
	v_pk_mul_f32 v[56:57], v[56:57], v[188:189]
	v_pk_mul_f32 v[52:53], v[52:53], v[212:213]
	v_pk_mul_f32 v[50:51], v[50:51], v[210:211]
	v_pk_mul_f32 v[46:47], v[46:47], v[152:153]
	v_pk_mul_f32 v[42:43], v[42:43], v[156:157]
	v_pk_mul_f32 v[38:39], v[38:39], v[186:187]
	v_pk_mul_f32 v[48:49], v[48:49], v[154:155]
	v_pk_mul_f32 v[44:45], v[44:45], v[158:159]
	v_pk_mul_f32 v[40:41], v[40:41], v[188:189]
	v_pk_mul_f32 v[36:37], v[36:37], v[212:213]
	v_pk_mul_f32 v[34:35], v[34:35], v[210:211]
	v_pk_mul_f32 v[30:31], v[30:31], v[152:153]
	v_pk_mul_f32 v[26:27], v[26:27], v[156:157]
	v_pk_mul_f32 v[22:23], v[22:23], v[186:187]
	v_pk_mul_f32 v[32:33], v[32:33], v[154:155]
	v_pk_mul_f32 v[28:29], v[28:29], v[158:159]
	v_pk_mul_f32 v[24:25], v[24:25], v[188:189]
	v_pk_mul_f32 v[20:21], v[20:21], v[212:213]
	v_pk_mul_f32 v[18:19], v[18:19], v[210:211]

; #define SBAR() __builtin_amdgcn_sched_barrier(0)
; __device__ __forceinline__ void finishSM(f32x16& p0, f32x16& p1, float alpha, float& l_reg, bf16x8& pa0, bf16x8& pa1, bf16x8& pa2, bf16x8& pa3) {
; #pragma unroll
;   for (int r = 0; r < 16; ++r) p1[r] = __builtin_amdgcn_exp2f(p1[r]);
;   float ps = 0;
; #pragma unroll
;   for (int r = 0; r < 16; ++r) ps += p0[r];
; #pragma unroll
;   for (int r = 0; r < 16; ++r) ps += p1[r];
;   { auto rr = __builtin_amdgcn_permlane32_swap(__float_as_uint(ps), __float_as_uint(ps), false, false);
;     ps = __uint_as_float(rr[0]) + __uint_as_float(rr[1]); }
;   l_reg = l_reg * alpha + ps;
;   PK4(p0, 0, pa0); PK4(p0, 8, pa1); PK4(p1, 0, pa2); PK4(p1, 8, pa3);
; }
;   p0 = f32x16{}; p1 = f32x16{};
; #pragma unroll
;   for (int d0 = DLO; d0 < DHI; ++d0) { int cb = (d0 * 16 + hi * 8) * 2;
;     bf16x8 b0 = *reinterpret_cast<const bf16x8*>((const char*)Ks + KSWZ(r32, cb));
;     bf16x8 b1 = *reinterpret_cast<const bf16x8*>((const char*)Ks + KSWZ(32 + r32, cb));
;     p0 = __builtin_amdgcn_mfma_f32_32x32x16_bf16(b0, qr[d0], p0, 0, 0, 0);
;     p1 = __builtin_amdgcn_mfma_f32_32x32x16_bf16(b1, qr[d0], p1, 0, 0, 0); }
; }
; template <int D0> __device__ __forceinline__ void pv_one(f32x16& od, int vb, bf16x8 pa0, bf16x8 pa1, bf16x8 pa2, bf16x8 pa3) {
;   const s16x4 l0 = tr_read<v_rd_off(D0, 0, 0)>(vb), h0 = tr_read<v_rd_off(D0, 0, 1)>(vb), l1 = tr_read<v_rd_off(D0, 1, 0)>(vb), h1 = tr_read<v_rd_off(D0, 1, 1)>(vb);
;   const s16x4 l2 = tr_read<v_rd_off(D0, 2, 0)>(vb), h2 = tr_read<v_rd_off(D0, 2, 1)>(vb), l3 = tr_read<v_rd_off(D0, 3, 0)>(vb), h3 = tr_read<v_rd_off(D0, 3, 1)>(vb);
;   asm volatile("s_waitcnt lgkmcnt(0)" ::: "memory"); SBAR();
;     ...
;   od = __builtin_amdgcn_mfma_f32_32x32x16_bf16(pa0, PK(l0, h0), od, 0, 0, 0);
;   od = __builtin_amdgcn_mfma_f32_32x32x16_bf16(pa1, PK(l1, h1), od, 0, 0, 0);
;   od = __builtin_amdgcn_mfma_f32_32x32x16_bf16(pa2, PK(l2, h2), od, 0, 0, 0);
;   od = __builtin_amdgcn_mfma_f32_32x32x16_bf16(pa3, PK(l3, h3), od, 0, 0, 0);
.LBB0_1022:
	ds_read_b128 v[66:69], v177 offset:49152
	ds_read_b128 v[70:73], v177 offset:57344
	ds_read_b128 v[186:189], v194 offset:49152
	ds_read_b128 v[208:211], v194 offset:57344
	ds_read_b128 v[232:235], v195 offset:49152
	ds_read_b128 v[236:239], v195 offset:57344
	ds_read_b128 v[240:243], v196 offset:49152
	ds_read_b128 v[244:247], v196 offset:57344
	v_add_f32_e32 v146, 0, v161
	v_add_f32_e32 v146, v167, v146
	v_add_f32_e32 v146, v147, v146
	s_waitcnt lgkmcnt(7)
	v_mfma_f32_32x32x16_bf16 v[82:97], v[66:69], v[102:105], 0
	v_add_f32_e32 v146, v166, v146
	v_add_f32_e32 v146, v148, v146
	v_add_f32_e32 v146, v160, v146
	v_add_f32_e32 v146, v149, v146
	v_add_f32_e32 v146, v159, v146
	v_add_f32_e32 v146, v156, v146
	s_waitcnt lgkmcnt(6)
	v_mfma_f32_32x32x16_bf16 v[66:81], v[70:73], v[102:105], 0
	v_add_f32_e32 v146, v158, v146
	v_add_f32_e32 v146, v154, v146
	v_add_f32_e32 v146, v157, v146
	v_exp_f32_e32 v142, v142
	v_add_f32_e32 v146, v152, v146
	v_exp_f32_e32 v143, v143
	v_add_f32_e32 v146, v155, v146
	s_waitcnt lgkmcnt(5)
	v_mfma_f32_32x32x16_bf16 v[82:97], v[186:189], v[98:101], v[82:97]
	v_exp_f32_e32 v140, v140
	v_add_f32_e32 v146, v151, v146
	v_exp_f32_e32 v141, v141
	v_add_f32_e32 v146, v153, v146
	v_exp_f32_e32 v134, v134
	v_add_f32_e32 v146, v142, v146
	v_exp_f32_e32 v135, v135
	s_waitcnt lgkmcnt(4)
	v_mfma_f32_32x32x16_bf16 v[66:81], v[208:211], v[98:101], v[66:81]
	v_add_f32_e32 v146, v143, v146
	v_exp_f32_e32 v132, v132
	v_add_f32_e32 v146, v140, v146
	v_exp_f32_e32 v133, v133
	v_add_f32_e32 v146, v141, v146
	v_exp_f32_e32 v130, v130
	s_waitcnt lgkmcnt(3)
	v_mfma_f32_32x32x16_bf16 v[82:97], v[232:235], v[106:109], v[82:97]
	v_add_f32_e32 v146, v134, v146
	v_exp_f32_e32 v131, v131
	v_add_f32_e32 v146, v135, v146
	v_exp_f32_e32 v144, v144
	v_add_f32_e32 v146, v132, v146
	v_exp_f32_e32 v145, v145
	v_add_f32_e32 v146, v133, v146
	s_waitcnt lgkmcnt(2)
	v_mfma_f32_32x32x16_bf16 v[66:81], v[236:239], v[106:109], v[66:81]
	v_exp_f32_e32 v138, v138
	v_add_f32_e32 v146, v130, v146
	v_exp_f32_e32 v139, v139
	v_add_f32_e32 v146, v131, v146
	v_exp_f32_e32 v136, v136
	v_add_f32_e32 v146, v144, v146
	s_waitcnt lgkmcnt(1)
	v_mfma_f32_32x32x16_bf16 v[82:97], v[240:243], v[110:113], v[82:97]
	v_exp_f32_e32 v137, v137
	v_add_f32_e32 v146, v145, v146
	v_add_f32_e32 v146, v138, v146
	v_add_f32_e32 v146, v139, v146
	v_add_f32_e32 v146, v136, v146
	v_add_f32_e32 v207, v137, v146
	v_cvt_pk_bf16_f32 v146, v161, v167
	s_waitcnt lgkmcnt(0)
	v_mfma_f32_32x32x16_bf16 v[66:81], v[244:247], v[110:113], v[66:81]
	v_mov_b32_e32 v208, v207
	v_cvt_pk_bf16_f32 v147, v147, v166
	v_cvt_pk_bf16_f32 v148, v148, v160
	s_nop 1
	v_permlane32_swap_b32_e32 v207, v208
	v_cvt_pk_bf16_f32 v149, v149, v159
	v_permlane32_swap_b32_e32 v146, v148
	v_cvt_pk_bf16_f32 v156, v156, v158
	v_cvt_pk_bf16_f32 v157, v154, v157
	v_cvt_pk_bf16_f32 v158, v152, v155
	v_cvt_pk_bf16_f32 v159, v151, v153
	v_cvt_pk_bf16_f32 v152, v142, v143
	v_cvt_pk_bf16_f32 v153, v140, v141
	v_cvt_pk_bf16_f32 v154, v134, v135
	v_cvt_pk_bf16_f32 v155, v132, v133
	v_cvt_pk_bf16_f32 v186, v130, v131
	v_cvt_pk_bf16_f32 v187, v144, v145
	v_cvt_pk_bf16_f32 v188, v138, v139
	v_cvt_pk_bf16_f32 v189, v136, v137
	v_permlane32_swap_b32_e32 v147, v149
	v_permlane32_swap_b32_e32 v156, v158
	v_permlane32_swap_b32_e32 v157, v159
	v_permlane32_swap_b32_e32 v152, v154
	v_permlane32_swap_b32_e32 v153, v155
	v_permlane32_swap_b32_e32 v186, v188
	v_permlane32_swap_b32_e32 v187, v189
	ds_read_b64_tr_b16 v[210:211], v176 offset:0
	ds_read_b64_tr_b16 v[212:213], v176 offset:0x800
	ds_read_b64_tr_b16 v[214:215], v176 offset:0x1000
	ds_read_b64_tr_b16 v[216:217], v176 offset:0x1800
	ds_read_b64_tr_b16 v[218:219], v176 offset:0x2000
	ds_read_b64_tr_b16 v[220:221], v176 offset:0x2800
	ds_read_b64_tr_b16 v[222:223], v176 offset:0x3000
	ds_read_b64_tr_b16 v[224:225], v176 offset:0x3800
	s_waitcnt vmcnt(0)
	ds_write_b128 v192, v[114:117]
	ds_write_b128 v193, v[118:121]
	ds_write_b128 v190, v[122:125] offset:32768
	ds_write_b128 v191, v[126:129] offset:32768
	v_lshl_add_u64 v[168:169], v[164:165], 0, v[0:1]
	s_mov_b32 s1, 0x18fb0000
	v_add_co_u32_e32 v130, vcc, s1, v168
	s_mov_b32 s1, 0x18ff8000
	s_nop 0
	v_addc_co_u32_e32 v131, vcc, 0, v169, vcc
	v_add_co_u32_e32 v134, vcc, s1, v168
	v_lshl_add_u64 v[166:167], v[162:163], 0, v[0:1]
	s_nop 0
	v_addc_co_u32_e32 v135, vcc, 0, v169, vcc
	s_mov_b32 s1, 0x1f648000
	v_add_co_u32_e32 v138, vcc, s1, v166
	s_mov_b32 s1, 0x1f654000
	s_nop 0
	v_addc_co_u32_e32 v139, vcc, 0, v167, vcc
	v_add_co_u32_e32 v142, vcc, s1, v166
	global_load_dwordx4 v[130:133], v[130:131], off
	s_nop 0
	global_load_dwordx4 v[134:137], v[134:135], off
	v_addc_co_u32_e32 v143, vcc, 0, v167, vcc
	global_load_dwordx4 v[138:141], v[138:139], off
	s_nop 0
	global_load_dwordx4 v[142:145], v[142:143], off
	s_waitcnt lgkmcnt(8)
	s_nop 0
	v_mfma_f32_32x32x16_bf16 v[2:17], v[146:149], v[210:213], v[2:17]
	ds_read_b64_tr_b16 v[210:211], v176 offset:0x200
	ds_read_b64_tr_b16 v[212:213], v176 offset:0xa00
	v_mfma_f32_32x32x16_bf16 v[2:17], v[156:159], v[214:217], v[2:17]
	ds_read_b64_tr_b16 v[214:215], v176 offset:0x1200
	ds_read_b64_tr_b16 v[216:217], v176 offset:0x1a00
	s_waitcnt lgkmcnt(8)
; #define SBAR() __builtin_amdgcn_sched_barrier(0)
; __device__ __forceinline__ void partialSM(f32x16& p0, f32x16& p1, float& m_reg, float& mn, float& alpha) {
;   constexpr float C = SCALE * 1.4426950408889634f;
;   float pmax = p0[0];
; #pragma unroll
;   for (int r = 1; r < 16; ++r) pmax = fmaxf(pmax, p0[r]);
; #pragma unroll
;   for (int r = 0; r < 16; ++r) pmax = fmaxf(pmax, p1[r]);
;   { auto rr = __builtin_amdgcn_permlane32_swap(__float_as_uint(pmax), __float_as_uint(pmax), false, false);
;     pmax = fmaxf(__uint_as_float(rr[0]), __uint_as_float(rr[1])); }
;   if (__builtin_expect(__all(pmax - m_reg <= THR / SCALE), 1)) { mn = m_reg; alpha = 1.f; }
;   else { mn = fmaxf(m_reg, pmax); alpha = __builtin_amdgcn_exp2f((m_reg - mn) * C); m_reg = mn; }
; template <int D0> __device__ __forceinline__ void pv_one(f32x16& od, int vb, bf16x8 pa0, bf16x8 pa1, bf16x8 pa2, bf16x8 pa3) {
;   const s16x4 l0 = tr_read<v_rd_off(D0, 0, 0)>(vb), h0 = tr_read<v_rd_off(D0, 0, 1)>(vb), l1 = tr_read<v_rd_off(D0, 1, 0)>(vb), h1 = tr_read<v_rd_off(D0, 1, 1)>(vb);
;   const s16x4 l2 = tr_read<v_rd_off(D0, 2, 0)>(vb), h2 = tr_read<v_rd_off(D0, 2, 1)>(vb), l3 = tr_read<v_rd_off(D0, 3, 0)>(vb), h3 = tr_read<v_rd_off(D0, 3, 1)>(vb);
;   asm volatile("s_waitcnt lgkmcnt(0)" ::: "memory"); SBAR();
;     ...
;   od = __builtin_amdgcn_mfma_f32_32x32x16_bf16(pa0, PK(l0, h0), od, 0, 0, 0);
;   od = __builtin_amdgcn_mfma_f32_32x32x16_bf16(pa1, PK(l1, h1), od, 0, 0, 0);
;   od = __builtin_amdgcn_mfma_f32_32x32x16_bf16(pa2, PK(l2, h2), od, 0, 0, 0);
;   od = __builtin_amdgcn_mfma_f32_32x32x16_bf16(pa3, PK(l3, h3), od, 0, 0, 0);
;     ...
; }
; __device__ __forceinline__ void pv_d0(f32x16* o, int vb, bf16x8 pa0, bf16x8 pa1, bf16x8 pa2, bf16x8 pa3) {
;   pv_one<0>(o[0], vb, pa0, pa1, pa2, pa3); pv_one<1>(o[1], vb, pa0, pa1, pa2, pa3); pv_one<2>(o[2], vb, pa0, pa1, pa2, pa3); pv_one<3>(o[3], vb, pa0, pa1, pa2, pa3);
	v_mfma_f32_32x32x16_bf16 v[2:17], v[152:155], v[218:221], v[2:17]
	ds_read_b64_tr_b16 v[218:219], v176 offset:0x2200
	ds_read_b64_tr_b16 v[220:221], v176 offset:0x2a00
	v_mfma_f32_32x32x16_bf16 v[2:17], v[186:189], v[222:225], v[2:17]
	ds_read_b64_tr_b16 v[222:223], v176 offset:0x3200
	ds_read_b64_tr_b16 v[224:225], v176 offset:0x3a00
	s_waitcnt lgkmcnt(4)
	v_mfma_f32_32x32x16_bf16 v[50:65], v[146:149], v[210:213], v[50:65]
	ds_read_b64_tr_b16 v[210:211], v176 offset:0x400
	ds_read_b64_tr_b16 v[212:213], v176 offset:0xc00
	v_mfma_f32_32x32x16_bf16 v[50:65], v[156:159], v[214:217], v[50:65]
	ds_read_b64_tr_b16 v[214:215], v176 offset:0x1400
	ds_read_b64_tr_b16 v[216:217], v176 offset:0x1c00
	s_waitcnt lgkmcnt(4)
	v_mfma_f32_32x32x16_bf16 v[50:65], v[152:155], v[218:221], v[50:65]
	ds_read_b64_tr_b16 v[218:219], v176 offset:0x2400
	ds_read_b64_tr_b16 v[220:221], v176 offset:0x2c00
	v_mfma_f32_32x32x16_bf16 v[50:65], v[186:189], v[222:225], v[50:65]
	ds_read_b64_tr_b16 v[222:223], v176 offset:0x3400
	ds_read_b64_tr_b16 v[224:225], v176 offset:0x3c00
	s_waitcnt lgkmcnt(4)
	v_mfma_f32_32x32x16_bf16 v[34:49], v[146:149], v[210:213], v[34:49]
	ds_read_b64_tr_b16 v[210:211], v176 offset:0x600
	ds_read_b64_tr_b16 v[212:213], v176 offset:0xe00
	v_mfma_f32_32x32x16_bf16 v[34:49], v[156:159], v[214:217], v[34:49]
	ds_read_b64_tr_b16 v[214:215], v176 offset:0x1600
	ds_read_b64_tr_b16 v[216:217], v176 offset:0x1e00
	s_waitcnt lgkmcnt(4)
	v_mfma_f32_32x32x16_bf16 v[34:49], v[152:155], v[218:221], v[34:49]
	ds_read_b64_tr_b16 v[218:219], v176 offset:0x2600
	ds_read_b64_tr_b16 v[220:221], v176 offset:0x2e00
	v_mfma_f32_32x32x16_bf16 v[34:49], v[186:189], v[222:225], v[34:49]
	ds_read_b64_tr_b16 v[222:223], v176 offset:0x3600
	ds_read_b64_tr_b16 v[224:225], v176 offset:0x3e00
	s_waitcnt lgkmcnt(4)
	v_mfma_f32_32x32x16_bf16 v[18:33], v[146:149], v[210:213], v[18:33]
	v_max_f32_e32 v146, v83, v83
	v_max_f32_e32 v147, v82, v82
	v_max_f32_e32 v146, v147, v146
	v_max3_f32 v146, v146, v84, v85
	v_max3_f32 v146, v146, v86, v87
	v_max3_f32 v146, v146, v88, v89
	v_max3_f32 v146, v146, v90, v91
	v_max3_f32 v146, v146, v92, v93
	v_max3_f32 v146, v146, v94, v95
	v_mfma_f32_32x32x16_bf16 v[18:33], v[156:159], v[214:217], v[18:33]
	v_max3_f32 v146, v146, v96, v97
	v_max3_f32 v146, v146, v66, v67
	v_max3_f32 v146, v146, v68, v69
	v_max3_f32 v146, v146, v70, v71
	v_max3_f32 v146, v146, v72, v73
	v_max3_f32 v146, v146, v74, v75
	v_max3_f32 v146, v146, v76, v77
	v_max3_f32 v146, v146, v78, v79
	s_waitcnt lgkmcnt(0)
	v_mfma_f32_32x32x16_bf16 v[18:33], v[152:155], v[218:221], v[18:33]
	v_max3_f32 v146, v146, v80, v81
	v_mov_b32_e32 v147, v146
	s_nop 1
	v_permlane32_swap_b32_e32 v146, v147
	v_max_f32_e32 v147, v147, v147
	v_max_f32_e32 v146, v146, v146
	v_max_f32_e32 v146, v146, v147
	v_sub_f32_e32 v147, v146, v150
	v_cmp_ge_f32_e32 vcc, s63, v147
	v_max_f32_e32 v147, v150, v150
	v_max_f32_e32 v146, v147, v146
	v_mfma_f32_32x32x16_bf16 v[18:33], v[186:189], v[222:225], v[18:33]
	v_sub_f32_e32 v147, v150, v146
	v_mul_f32_e32 v147, 0x3e0293ee, v147
	v_exp_f32_e32 v147, v147
	s_cmp_eq_u64 vcc, exec
	s_cselect_b64 s[8:9], -1, 0
	s_waitcnt vmcnt(4)
	v_cndmask_b32_e64 v209, v147, 1.0, s[8:9]
	v_cmp_gt_f32_e32 vcc, 1.0, v209
	s_cbranch_vccz .LBB0_1026
	s_and_saveexec_b64 s[2:3], s[6:7]
	ds_write_b32 v173, v209 offset:128
	s_or_b64 exec, exec, s[2:3]
	s_waitcnt lgkmcnt(0)
	v_add_u32_e32 v147, s15, v172
	ds_read_b128 v[152:155], v147 offset:224
	ds_read_b128 v[156:159], v147 offset:192
	ds_read_b128 v[186:189], v147 offset:160
	ds_read_b128 v[210:213], v147 offset:128
	s_waitcnt lgkmcnt(3)
	v_pk_mul_f32 v[14:15], v[14:15], v[152:153]
	s_waitcnt lgkmcnt(2)
	v_pk_mul_f32 v[10:11], v[10:11], v[156:157]
	s_waitcnt lgkmcnt(1)
	v_pk_mul_f32 v[6:7], v[6:7], v[186:187]
	v_pk_mul_f32 v[16:17], v[16:17], v[154:155]
	v_pk_mul_f32 v[12:13], v[12:13], v[158:159]
	v_pk_mul_f32 v[8:9], v[8:9], v[188:189]
	s_waitcnt lgkmcnt(0)
	v_pk_mul_f32 v[4:5], v[4:5], v[212:213]
	v_pk_mul_f32 v[2:3], v[2:3], v[210:211]
	v_pk_mul_f32 v[62:63], v[62:63], v[152:153]
	v_pk_mul_f32 v[58:59], v[58:59], v[156:157]
	v_pk_mul_f32 v[54:55], v[54:55], v[186:187]
	v_pk_mul_f32 v[64:65], v[64:65], v[154:155]
	v_pk_mul_f32 v[60:61], v[60:61], v[158:159]
	v_pk_mul_f32 v[56:57], v[56:57], v[188:189]
	v_pk_mul_f32 v[52:53], v[52:53], v[212:213]
	v_pk_mul_f32 v[50:51], v[50:51], v[210:211]
	v_pk_mul_f32 v[46:47], v[46:47], v[152:153]
	v_pk_mul_f32 v[42:43], v[42:43], v[156:157]
	v_pk_mul_f32 v[38:39], v[38:39], v[186:187]
	v_pk_mul_f32 v[48:49], v[48:49], v[154:155]
	v_pk_mul_f32 v[44:45], v[44:45], v[158:159]
	v_pk_mul_f32 v[40:41], v[40:41], v[188:189]
	v_pk_mul_f32 v[36:37], v[36:37], v[212:213]
	v_pk_mul_f32 v[34:35], v[34:35], v[210:211]
	v_pk_mul_f32 v[30:31], v[30:31], v[152:153]
	v_pk_mul_f32 v[26:27], v[26:27], v[156:157]
	v_pk_mul_f32 v[22:23], v[22:23], v[186:187]
	v_pk_mul_f32 v[32:33], v[32:33], v[154:155]
	v_pk_mul_f32 v[28:29], v[28:29], v[158:159]
	v_pk_mul_f32 v[24:25], v[24:25], v[188:189]
	v_pk_mul_f32 v[20:21], v[20:21], v[212:213]
	v_pk_mul_f32 v[18:19], v[18:19], v[210:211]

; #define SBAR() __builtin_amdgcn_sched_barrier(0)
; __device__ __forceinline__ void finishSM(f32x16& p0, f32x16& p1, float alpha, float& l_reg, bf16x8& pa0, bf16x8& pa1, bf16x8& pa2, bf16x8& pa3) {
; #pragma unroll
;   for (int r = 0; r < 16; ++r) p1[r] = __builtin_amdgcn_exp2f(p1[r]);
;   float ps = 0;
; #pragma unroll
;   for (int r = 0; r < 16; ++r) ps += p0[r];
; #pragma unroll
;   for (int r = 0; r < 16; ++r) ps += p1[r];
;   { auto rr = __builtin_amdgcn_permlane32_swap(__float_as_uint(ps), __float_as_uint(ps), false, false);
;     ps = __uint_as_float(rr[0]) + __uint_as_float(rr[1]); }
;   l_reg = l_reg * alpha + ps;
;   PK4(p0, 0, pa0); PK4(p0, 8, pa1); PK4(p1, 0, pa2); PK4(p1, 8, pa3);
; }
;   p0 = f32x16{}; p1 = f32x16{};
; #pragma unroll
;   for (int d0 = DLO; d0 < DHI; ++d0) { int cb = (d0 * 16 + hi * 8) * 2;
;     bf16x8 b0 = *reinterpret_cast<const bf16x8*>((const char*)Ks + KSWZ(r32, cb));
;     bf16x8 b1 = *reinterpret_cast<const bf16x8*>((const char*)Ks + KSWZ(32 + r32, cb));
;     p0 = __builtin_amdgcn_mfma_f32_32x32x16_bf16(b0, qr[d0], p0, 0, 0, 0);
;     p1 = __builtin_amdgcn_mfma_f32_32x32x16_bf16(b1, qr[d0], p1, 0, 0, 0); }
; }
; template <int D0> __device__ __forceinline__ void pv_one(f32x16& od, int vb, bf16x8 pa0, bf16x8 pa1, bf16x8 pa2, bf16x8 pa3) {
;   const s16x4 l0 = tr_read<v_rd_off(D0, 0, 0)>(vb), h0 = tr_read<v_rd_off(D0, 0, 1)>(vb), l1 = tr_read<v_rd_off(D0, 1, 0)>(vb), h1 = tr_read<v_rd_off(D0, 1, 1)>(vb);
;   const s16x4 l2 = tr_read<v_rd_off(D0, 2, 0)>(vb), h2 = tr_read<v_rd_off(D0, 2, 1)>(vb), l3 = tr_read<v_rd_off(D0, 3, 0)>(vb), h3 = tr_read<v_rd_off(D0, 3, 1)>(vb);
;   asm volatile("s_waitcnt lgkmcnt(0)" ::: "memory"); SBAR();
;     ...
;   od = __builtin_amdgcn_mfma_f32_32x32x16_bf16(pa0, PK(l0, h0), od, 0, 0, 0);
;   od = __builtin_amdgcn_mfma_f32_32x32x16_bf16(pa1, PK(l1, h1), od, 0, 0, 0);
;   od = __builtin_amdgcn_mfma_f32_32x32x16_bf16(pa2, PK(l2, h2), od, 0, 0, 0);
;   od = __builtin_amdgcn_mfma_f32_32x32x16_bf16(pa3, PK(l3, h3), od, 0, 0, 0);
.LBB0_1043:
	ds_read_b128 v[66:69], v218 offset:49152
	ds_read_b128 v[70:73], v218 offset:57344
	ds_read_b128 v[186:189], v225 offset:49152
	ds_read_b128 v[230:233], v225 offset:57344
	ds_read_b128 v[234:237], v224 offset:49152
	ds_read_b128 v[238:241], v224 offset:57344
	ds_read_b128 v[242:245], v222 offset:49152
	ds_read_b128 v[246:249], v222 offset:57344
	v_add_f32_e32 v162, 0, v177
	v_add_f32_e32 v162, v195, v162
	s_waitcnt lgkmcnt(7)
	v_mfma_f32_32x32x16_bf16 v[82:97], v[66:69], v[118:121], 0
	v_add_f32_e32 v162, v163, v162
	v_add_f32_e32 v162, v194, v162
	v_add_f32_e32 v162, v164, v162
	v_add_f32_e32 v162, v176, v162
	v_add_f32_e32 v162, v165, v162
	v_add_f32_e32 v162, v175, v162
	v_add_f32_e32 v162, v166, v162
	s_waitcnt lgkmcnt(6)
	v_mfma_f32_32x32x16_bf16 v[66:81], v[70:73], v[118:121], 0
	v_add_f32_e32 v162, v174, v162
	v_add_f32_e32 v162, v167, v162
	v_add_f32_e32 v162, v173, v162
	v_exp_f32_e32 v158, v158
	v_add_f32_e32 v162, v168, v162
	v_exp_f32_e32 v159, v159
	v_add_f32_e32 v162, v172, v162
	s_waitcnt lgkmcnt(5)
	v_mfma_f32_32x32x16_bf16 v[82:97], v[186:189], v[110:113], v[82:97]
	v_exp_f32_e32 v156, v156
	v_add_f32_e32 v162, v169, v162
	v_exp_f32_e32 v157, v157
	v_add_f32_e32 v162, v171, v162
	v_exp_f32_e32 v150, v150
	v_add_f32_e32 v162, v158, v162
	v_exp_f32_e32 v151, v151
	s_waitcnt lgkmcnt(4)
	v_mfma_f32_32x32x16_bf16 v[66:81], v[230:233], v[110:113], v[66:81]
	ds_read_b128 v[186:189], v220 offset:49152
	ds_read_b128 v[230:233], v220 offset:57344
	v_add_f32_e32 v162, v159, v162
	v_exp_f32_e32 v148, v148
	v_add_f32_e32 v162, v156, v162
	v_exp_f32_e32 v149, v149
	v_add_f32_e32 v162, v157, v162
	v_exp_f32_e32 v146, v146
	s_waitcnt lgkmcnt(5)
	v_mfma_f32_32x32x16_bf16 v[82:97], v[234:237], v[126:129], v[82:97]
	v_add_f32_e32 v162, v150, v162
	v_exp_f32_e32 v147, v147
	v_add_f32_e32 v162, v151, v162
	v_exp_f32_e32 v160, v160
	v_add_f32_e32 v162, v148, v162
	v_exp_f32_e32 v161, v161
	v_add_f32_e32 v162, v149, v162
	s_waitcnt lgkmcnt(4)
	v_mfma_f32_32x32x16_bf16 v[66:81], v[238:241], v[126:129], v[66:81]
	ds_read_b128 v[234:237], v219 offset:49152
	ds_read_b128 v[238:241], v219 offset:57344
	v_exp_f32_e32 v154, v154
	v_add_f32_e32 v162, v146, v162
	v_exp_f32_e32 v155, v155
	v_add_f32_e32 v162, v147, v162
	v_exp_f32_e32 v152, v152
	v_add_f32_e32 v162, v160, v162
	s_waitcnt lgkmcnt(5)
	v_mfma_f32_32x32x16_bf16 v[82:97], v[242:245], v[122:125], v[82:97]
	v_exp_f32_e32 v153, v153
	v_add_f32_e32 v162, v161, v162
	v_add_f32_e32 v162, v154, v162
	v_add_f32_e32 v162, v155, v162
	v_add_f32_e32 v162, v152, v162
	v_add_f32_e32 v227, v153, v162
	s_waitcnt lgkmcnt(4)
	v_mfma_f32_32x32x16_bf16 v[66:81], v[246:249], v[122:125], v[66:81]
	ds_read_b128 v[242:245], v221 offset:49152
	ds_read_b128 v[246:249], v221 offset:57344
	s_waitcnt lgkmcnt(5)
	v_mfma_f32_32x32x16_bf16 v[82:97], v[186:189], v[114:117], v[82:97]
	s_waitcnt lgkmcnt(4)
	v_mfma_f32_32x32x16_bf16 v[66:81], v[230:233], v[114:117], v[66:81]
	ds_read_b128 v[186:189], v223 offset:49152
	ds_read_b128 v[230:233], v223 offset:57344
	s_waitcnt lgkmcnt(5)
	v_mfma_f32_32x32x16_bf16 v[82:97], v[234:237], v[106:109], v[82:97]
	s_waitcnt lgkmcnt(4)
	v_mfma_f32_32x32x16_bf16 v[66:81], v[238:241], v[106:109], v[66:81]
	s_waitcnt lgkmcnt(3)
	v_mfma_f32_32x32x16_bf16 v[82:97], v[242:245], v[102:105], v[82:97]
	s_waitcnt lgkmcnt(2)
	v_mfma_f32_32x32x16_bf16 v[66:81], v[246:249], v[102:105], v[66:81]
	v_cvt_pk_bf16_f32 v162, v177, v195
	v_cvt_pk_bf16_f32 v163, v163, v194
	v_cvt_pk_bf16_f32 v164, v164, v176
	v_cvt_pk_bf16_f32 v165, v165, v175
	v_cvt_pk_bf16_f32 v166, v166, v174
	v_cvt_pk_bf16_f32 v167, v167, v173
	s_waitcnt lgkmcnt(1)
	v_mfma_f32_32x32x16_bf16 v[82:97], v[186:189], v[98:101], v[82:97]
	v_mov_b32_e32 v228, v227
	s_nop 1
	v_permlane32_swap_b32_e32 v227, v228
	v_permlane32_swap_b32_e32 v162, v164
	v_cvt_pk_bf16_f32 v168, v168, v172
	v_cvt_pk_bf16_f32 v169, v169, v171
	s_waitcnt lgkmcnt(0)
	v_mfma_f32_32x32x16_bf16 v[66:81], v[230:233], v[98:101], v[66:81]
	v_cvt_pk_bf16_f32 v172, v158, v159
	v_cvt_pk_bf16_f32 v173, v156, v157
	v_cvt_pk_bf16_f32 v174, v150, v151
	v_cvt_pk_bf16_f32 v175, v148, v149
	v_cvt_pk_bf16_f32 v230, v146, v147
	v_cvt_pk_bf16_f32 v231, v160, v161
	v_cvt_pk_bf16_f32 v232, v154, v155
	v_cvt_pk_bf16_f32 v233, v152, v153
	v_permlane32_swap_b32_e32 v163, v165
	v_permlane32_swap_b32_e32 v166, v168
	v_permlane32_swap_b32_e32 v167, v169
	v_permlane32_swap_b32_e32 v172, v174
	v_permlane32_swap_b32_e32 v173, v175
	v_permlane32_swap_b32_e32 v230, v232
	v_permlane32_swap_b32_e32 v231, v233
	ds_read_b64_tr_b16 v[234:235], v213 offset:0
	ds_read_b64_tr_b16 v[236:237], v213 offset:0x800
	ds_read_b64_tr_b16 v[238:239], v213 offset:0x1000
	ds_read_b64_tr_b16 v[240:241], v213 offset:0x1800
	ds_read_b64_tr_b16 v[242:243], v213 offset:0x2000
	ds_read_b64_tr_b16 v[244:245], v213 offset:0x2800
	ds_read_b64_tr_b16 v[246:247], v213 offset:0x3000
	ds_read_b64_tr_b16 v[248:249], v213 offset:0x3800
	s_waitcnt vmcnt(0)
	ds_write_b128 v216, v[130:133]
	ds_write_b128 v217, v[134:137]
	ds_write_b128 v214, v[138:141] offset:32768
	ds_write_b128 v215, v[142:145] offset:32768
	v_lshl_add_u64 v[196:197], v[192:193], 0, v[0:1]
	s_mov_b32 s1, 0x18fb0000
	v_add_co_u32_e32 v146, vcc, s1, v196
	s_mov_b32 s1, 0x18ff8000
	s_nop 0
	v_addc_co_u32_e32 v147, vcc, 0, v197, vcc
	v_add_co_u32_e32 v150, vcc, s1, v196
	v_lshl_add_u64 v[194:195], v[190:191], 0, v[0:1]
	s_nop 0
	v_addc_co_u32_e32 v151, vcc, 0, v197, vcc
	s_mov_b32 s1, 0x1f648000
	v_add_co_u32_e32 v154, vcc, s1, v194
	s_mov_b32 s1, 0x1f654000
	s_nop 0
	v_addc_co_u32_e32 v155, vcc, 0, v195, vcc
	v_add_co_u32_e32 v158, vcc, s1, v194
	global_load_dwordx4 v[146:149], v[146:147], off
	s_nop 0
	global_load_dwordx4 v[150:153], v[150:151], off
	v_addc_co_u32_e32 v159, vcc, 0, v195, vcc
	global_load_dwordx4 v[154:157], v[154:155], off
	s_nop 0
	global_load_dwordx4 v[158:161], v[158:159], off
	s_waitcnt lgkmcnt(8)
; #define SBAR() __builtin_amdgcn_sched_barrier(0)
; __device__ __forceinline__ void partialSM(f32x16& p0, f32x16& p1, float& m_reg, float& mn, float& alpha) {
;   constexpr float C = SCALE * 1.4426950408889634f;
;   float pmax = p0[0];
; #pragma unroll
;   for (int r = 1; r < 16; ++r) pmax = fmaxf(pmax, p0[r]);
; #pragma unroll
;   for (int r = 0; r < 16; ++r) pmax = fmaxf(pmax, p1[r]);
;   { auto rr = __builtin_amdgcn_permlane32_swap(__float_as_uint(pmax), __float_as_uint(pmax), false, false);
;     pmax = fmaxf(__uint_as_float(rr[0]), __uint_as_float(rr[1])); }
;   if (__builtin_expect(__all(pmax - m_reg <= THR / SCALE), 1)) { mn = m_reg; alpha = 1.f; }
;   else { mn = fmaxf(m_reg, pmax); alpha = __builtin_amdgcn_exp2f((m_reg - mn) * C); m_reg = mn; }
; template <int D0> __device__ __forceinline__ void pv_one(f32x16& od, int vb, bf16x8 pa0, bf16x8 pa1, bf16x8 pa2, bf16x8 pa3) {
;   const s16x4 l0 = tr_read<v_rd_off(D0, 0, 0)>(vb), h0 = tr_read<v_rd_off(D0, 0, 1)>(vb), l1 = tr_read<v_rd_off(D0, 1, 0)>(vb), h1 = tr_read<v_rd_off(D0, 1, 1)>(vb);
;   const s16x4 l2 = tr_read<v_rd_off(D0, 2, 0)>(vb), h2 = tr_read<v_rd_off(D0, 2, 1)>(vb), l3 = tr_read<v_rd_off(D0, 3, 0)>(vb), h3 = tr_read<v_rd_off(D0, 3, 1)>(vb);
;   asm volatile("s_waitcnt lgkmcnt(0)" ::: "memory"); SBAR();
;     ...
;   od = __builtin_amdgcn_mfma_f32_32x32x16_bf16(pa0, PK(l0, h0), od, 0, 0, 0);
;   od = __builtin_amdgcn_mfma_f32_32x32x16_bf16(pa1, PK(l1, h1), od, 0, 0, 0);
;   od = __builtin_amdgcn_mfma_f32_32x32x16_bf16(pa2, PK(l2, h2), od, 0, 0, 0);
;   od = __builtin_amdgcn_mfma_f32_32x32x16_bf16(pa3, PK(l3, h3), od, 0, 0, 0);
;     ...
; }
; __device__ __forceinline__ void pv_d0(f32x16* o, int vb, bf16x8 pa0, bf16x8 pa1, bf16x8 pa2, bf16x8 pa3) {
;   pv_one<0>(o[0], vb, pa0, pa1, pa2, pa3); pv_one<1>(o[1], vb, pa0, pa1, pa2, pa3); pv_one<2>(o[2], vb, pa0, pa1, pa2, pa3); pv_one<3>(o[3], vb, pa0, pa1, pa2, pa3);
	s_nop 0
	v_mfma_f32_32x32x16_bf16 v[2:17], v[162:165], v[234:237], v[2:17]
	ds_read_b64_tr_b16 v[234:235], v213 offset:0x200
	ds_read_b64_tr_b16 v[236:237], v213 offset:0xa00
	v_mfma_f32_32x32x16_bf16 v[2:17], v[166:169], v[238:241], v[2:17]
	ds_read_b64_tr_b16 v[238:239], v213 offset:0x1200
	ds_read_b64_tr_b16 v[240:241], v213 offset:0x1a00
	s_waitcnt lgkmcnt(8)
	v_mfma_f32_32x32x16_bf16 v[2:17], v[172:175], v[242:245], v[2:17]
	ds_read_b64_tr_b16 v[242:243], v213 offset:0x2200
	ds_read_b64_tr_b16 v[244:245], v213 offset:0x2a00
	v_mfma_f32_32x32x16_bf16 v[2:17], v[230:233], v[246:249], v[2:17]
	ds_read_b64_tr_b16 v[246:247], v213 offset:0x3200
	ds_read_b64_tr_b16 v[248:249], v213 offset:0x3a00
	s_waitcnt lgkmcnt(4)
	v_mfma_f32_32x32x16_bf16 v[50:65], v[162:165], v[234:237], v[50:65]
	ds_read_b64_tr_b16 v[234:235], v213 offset:0x400
	ds_read_b64_tr_b16 v[236:237], v213 offset:0xc00
	v_mfma_f32_32x32x16_bf16 v[50:65], v[166:169], v[238:241], v[50:65]
	ds_read_b64_tr_b16 v[238:239], v213 offset:0x1400
	ds_read_b64_tr_b16 v[240:241], v213 offset:0x1c00
	s_waitcnt lgkmcnt(4)
	v_mfma_f32_32x32x16_bf16 v[50:65], v[172:175], v[242:245], v[50:65]
	ds_read_b64_tr_b16 v[242:243], v213 offset:0x2400
	ds_read_b64_tr_b16 v[244:245], v213 offset:0x2c00
	v_mfma_f32_32x32x16_bf16 v[50:65], v[230:233], v[246:249], v[50:65]
	ds_read_b64_tr_b16 v[246:247], v213 offset:0x3400
	ds_read_b64_tr_b16 v[248:249], v213 offset:0x3c00
	s_waitcnt lgkmcnt(4)
	v_mfma_f32_32x32x16_bf16 v[34:49], v[162:165], v[234:237], v[34:49]
	ds_read_b64_tr_b16 v[234:235], v213 offset:0x600
	ds_read_b64_tr_b16 v[236:237], v213 offset:0xe00
	v_mfma_f32_32x32x16_bf16 v[34:49], v[166:169], v[238:241], v[34:49]
	ds_read_b64_tr_b16 v[238:239], v213 offset:0x1600
	ds_read_b64_tr_b16 v[240:241], v213 offset:0x1e00
	s_waitcnt lgkmcnt(4)
	v_mfma_f32_32x32x16_bf16 v[34:49], v[172:175], v[242:245], v[34:49]
	ds_read_b64_tr_b16 v[242:243], v213 offset:0x2600
	ds_read_b64_tr_b16 v[244:245], v213 offset:0x2e00
	v_mfma_f32_32x32x16_bf16 v[34:49], v[230:233], v[246:249], v[34:49]
	ds_read_b64_tr_b16 v[246:247], v213 offset:0x3600
	ds_read_b64_tr_b16 v[248:249], v213 offset:0x3e00
	s_waitcnt lgkmcnt(4)
	v_mfma_f32_32x32x16_bf16 v[18:33], v[162:165], v[234:237], v[18:33]
	v_max_f32_e32 v162, v83, v83
	v_max_f32_e32 v163, v82, v82
	v_max_f32_e32 v162, v163, v162
	v_max3_f32 v162, v162, v84, v85
	v_max3_f32 v162, v162, v86, v87
	v_max3_f32 v162, v162, v88, v89
	v_max3_f32 v162, v162, v90, v91
	v_max3_f32 v162, v162, v92, v93
	v_max3_f32 v162, v162, v94, v95
	v_mfma_f32_32x32x16_bf16 v[18:33], v[166:169], v[238:241], v[18:33]
	v_max3_f32 v162, v162, v96, v97
	v_max3_f32 v162, v162, v66, v67
	v_max3_f32 v162, v162, v68, v69
	v_max3_f32 v162, v162, v70, v71
	v_max3_f32 v162, v162, v72, v73
	v_max3_f32 v162, v162, v74, v75
	v_max3_f32 v162, v162, v76, v77
	v_max3_f32 v162, v162, v78, v79
	s_waitcnt lgkmcnt(0)
	v_mfma_f32_32x32x16_bf16 v[18:33], v[172:175], v[242:245], v[18:33]
	v_max3_f32 v162, v162, v80, v81
	v_mov_b32_e32 v163, v162
	s_nop 1
	v_permlane32_swap_b32_e32 v162, v163
	v_max_f32_e32 v163, v163, v163
	v_max_f32_e32 v162, v162, v162
	v_max_f32_e32 v162, v162, v163
	v_sub_f32_e32 v163, v162, v170
	v_cmp_ge_f32_e32 vcc, s63, v163
	v_max_f32_e32 v163, v170, v170
	v_max_f32_e32 v162, v163, v162
	v_mfma_f32_32x32x16_bf16 v[18:33], v[230:233], v[246:249], v[18:33]
	v_sub_f32_e32 v163, v170, v162
	v_mul_f32_e32 v163, 0x3e0293ee, v163
	v_exp_f32_e32 v163, v163
	s_cmp_eq_u64 vcc, exec
	s_cselect_b64 s[8:9], -1, 0
	s_waitcnt vmcnt(4)
	v_cndmask_b32_e64 v229, v163, 1.0, s[8:9]
	v_cmp_gt_f32_e32 vcc, 1.0, v229
	s_cbranch_vccz .LBB0_1047
	s_and_saveexec_b64 s[2:3], s[6:7]
	ds_write_b32 v210, v229 offset:128
	s_or_b64 exec, exec, s[2:3]
	s_waitcnt lgkmcnt(0)
	v_add_u32_e32 v163, s15, v209
	ds_read_b128 v[164:167], v163 offset:224
	ds_read_b128 v[172:175], v163 offset:192
	ds_read_b128 v[230:233], v163 offset:160
	ds_read_b128 v[234:237], v163 offset:128
	s_waitcnt lgkmcnt(3)
	v_pk_mul_f32 v[14:15], v[14:15], v[164:165]
	s_waitcnt lgkmcnt(2)
	v_pk_mul_f32 v[10:11], v[10:11], v[172:173]
	s_waitcnt lgkmcnt(1)
	v_pk_mul_f32 v[6:7], v[6:7], v[230:231]
	v_pk_mul_f32 v[16:17], v[16:17], v[166:167]
	v_pk_mul_f32 v[12:13], v[12:13], v[174:175]
	v_pk_mul_f32 v[8:9], v[8:9], v[232:233]
	s_waitcnt lgkmcnt(0)
	v_pk_mul_f32 v[4:5], v[4:5], v[236:237]
	v_pk_mul_f32 v[2:3], v[2:3], v[234:235]
	v_pk_mul_f32 v[62:63], v[62:63], v[164:165]
	v_pk_mul_f32 v[58:59], v[58:59], v[172:173]
	v_pk_mul_f32 v[54:55], v[54:55], v[230:231]
	v_pk_mul_f32 v[64:65], v[64:65], v[166:167]
	v_pk_mul_f32 v[60:61], v[60:61], v[174:175]
	v_pk_mul_f32 v[56:57], v[56:57], v[232:233]
	v_pk_mul_f32 v[52:53], v[52:53], v[236:237]
	v_pk_mul_f32 v[50:51], v[50:51], v[234:235]
	v_pk_mul_f32 v[46:47], v[46:47], v[164:165]
	v_pk_mul_f32 v[42:43], v[42:43], v[172:173]
	v_pk_mul_f32 v[38:39], v[38:39], v[230:231]
	v_pk_mul_f32 v[48:49], v[48:49], v[166:167]
	v_pk_mul_f32 v[44:45], v[44:45], v[174:175]
	v_pk_mul_f32 v[40:41], v[40:41], v[232:233]
	v_pk_mul_f32 v[36:37], v[36:37], v[236:237]
	v_pk_mul_f32 v[34:35], v[34:35], v[234:235]
	v_pk_mul_f32 v[30:31], v[30:31], v[164:165]
	v_pk_mul_f32 v[26:27], v[26:27], v[172:173]
	v_pk_mul_f32 v[22:23], v[22:23], v[230:231]
	v_pk_mul_f32 v[32:33], v[32:33], v[166:167]
	v_pk_mul_f32 v[28:29], v[28:29], v[174:175]
	v_pk_mul_f32 v[24:25], v[24:25], v[232:233]
	v_pk_mul_f32 v[20:21], v[20:21], v[236:237]
	v_pk_mul_f32 v[18:19], v[18:19], v[234:235]
